# out-proj epilogue: lanes fr and fr^8 exchange accumulator quads (DPP row_ror:8) so every x load and out store covers 8 rows x full 128-byte lines instead of 16 rows x 64-byte half lines
# speedup vs baseline: 1.0123x; 1.0093x over previous
;     __device__ __forceinline__ void operator()(const pg8::f32x4 (&acc)[2][2][4][2], const pg8::Unit& u, int wr, int wc, int fr, int fq) const {
;         const int row0 = u.pm * 256 + wr * 64 + fr, col0 = u.pn * 256 + wc * 32 + 4 * fq;
; #pragma unroll
;         for (int ai = 0; ai < 2; ++ai)
; #pragma unroll
;             for (int m = 0; m < 4; ++m) { const size_t off = (size_t)(row0 + ai * 128 + m * 16) * DM + col0;
; #pragma unroll
;                 for (int bj = 0; bj < 2; ++bj)
; #pragma unroll
;                     for (int n = 0; n < 2; ++n) { const size_t o2 = off + bj * 128 + n * 16; *(pg8::f32x4*)(out + o2) = *(const pg8::f32x4*)(x + o2) + acc[ai][bj][m][n]; }
;                 if (m & 1) asm volatile("" ::: "memory"); }
.LBB0_481:
	v_lshl_add_u32 v146, s26, 8, v136
	v_lshl_or_b32 v148, s55, 8, v138
	v_ashrrev_i32_e32 v147, 31, v146
	v_ashrrev_i32_e32 v149, 31, v148
	v_lshlrev_b64 v[134:135], 10, v[146:147]
	v_lshl_add_u64 v[134:135], v[134:135], 0, v[148:149]
	v_lshlrev_b64 v[134:135], 2, v[134:135]
	s_andn2_b64 vcc, exec, s[20:21]
	s_mov_b64 s[20:21], -1
	v_mbcnt_lo_u32_b32 v242, -1, 0
	v_mbcnt_hi_u32_b32 v242, -1, v242
	v_and_b32_e32 v242, 8, v242
	v_cmp_ne_u32_e64 s[94:95], 0, v242
	v_mul_u32_u24_e32 v242, 0xff8, v242
	v_sub_u32_e32 v134, v134, v242
	v_mov_b32_e32 v218, v134
	v_add_u32_e32 v219, 0x10000, v134
	v_add_u32_e32 v220, 0x20000, v134
	v_add_u32_e32 v221, 0x30000, v134
	v_add_u32_e32 v222, 0x80000, v134
	v_add_u32_e32 v223, 0x90000, v134
	v_add_u32_e32 v224, 0xa0000, v134
	v_add_u32_e32 v225, 0xb0000, v134
	v_add_u32_e32 v226, 0x8000, v134
	v_add_u32_e32 v227, 0x18000, v134
	v_add_u32_e32 v228, 0x28000, v134
	v_add_u32_e32 v229, 0x38000, v134
	v_add_u32_e32 v230, 0x88000, v134
	v_add_u32_e32 v231, 0x98000, v134
	v_add_u32_e32 v232, 0xa8000, v134
	v_add_u32_e32 v233, 0xb8000, v134
	global_load_dwordx4 v[142:145], v218, s[36:37]
	global_load_dwordx4 v[146:149], v226, s[36:37]
	global_load_dwordx4 v[156:159], v218, s[36:37] offset:512
	global_load_dwordx4 v[160:163], v226, s[36:37] offset:512
	global_load_dwordx4 v[164:167], v219, s[36:37]
	global_load_dwordx4 v[168:171], v227, s[36:37]
	global_load_dwordx4 v[172:175], v219, s[36:37] offset:512
	global_load_dwordx4 v[176:179], v227, s[36:37] offset:512
	global_load_dwordx4 v[180:183], v220, s[36:37]
	global_load_dwordx4 v[184:187], v228, s[36:37]
	global_load_dwordx4 v[188:191], v220, s[36:37] offset:512
	global_load_dwordx4 v[192:195], v228, s[36:37] offset:512
	global_load_dwordx4 v[196:199], v221, s[36:37]
	global_load_dwordx4 v[200:203], v229, s[36:37]
	global_load_dwordx4 v[204:207], v221, s[36:37] offset:512
	global_load_dwordx4 v[208:211], v229, s[36:37] offset:512
	v_cndmask_b32_e64 v234, v120, v124, s[94:95]
	v_cndmask_b32_e64 v235, v121, v125, s[94:95]
	v_cndmask_b32_e64 v236, v122, v126, s[94:95]
	v_cndmask_b32_e64 v237, v123, v127, s[94:95]
	v_mov_b32_dpp v238, v234 row_ror:8 row_mask:0xf bank_mask:0xf bound_ctrl:1
	v_mov_b32_dpp v239, v235 row_ror:8 row_mask:0xf bank_mask:0xf bound_ctrl:1
	v_mov_b32_dpp v240, v236 row_ror:8 row_mask:0xf bank_mask:0xf bound_ctrl:1
	v_mov_b32_dpp v241, v237 row_ror:8 row_mask:0xf bank_mask:0xf bound_ctrl:1
	v_cndmask_b32_e64 v124, v124, v238, s[94:95]
	v_cndmask_b32_e64 v125, v125, v239, s[94:95]
	v_cndmask_b32_e64 v126, v126, v240, s[94:95]
	v_cndmask_b32_e64 v127, v127, v241, s[94:95]
	v_cndmask_b32_e64 v120, v238, v120, s[94:95]
	v_cndmask_b32_e64 v121, v239, v121, s[94:95]
	v_cndmask_b32_e64 v122, v240, v122, s[94:95]
	v_cndmask_b32_e64 v123, v241, v123, s[94:95]
	s_waitcnt vmcnt(15)
	v_pk_add_f32 v[124:125], v[124:125], v[142:143]
	v_pk_add_f32 v[126:127], v[126:127], v[144:145]
	global_store_dwordx4 v218, v[124:127], s[50:51]
	global_load_dwordx4 v[142:145], v222, s[36:37]
	s_waitcnt vmcnt(16)
	v_pk_add_f32 v[120:121], v[120:121], v[146:147]
	v_pk_add_f32 v[122:123], v[122:123], v[148:149]
	global_store_dwordx4 v226, v[120:123], s[50:51]
	global_load_dwordx4 v[146:149], v230, s[36:37]
	v_cndmask_b32_e64 v234, v104, v116, s[94:95]
	v_cndmask_b32_e64 v235, v105, v117, s[94:95]
	v_cndmask_b32_e64 v236, v106, v118, s[94:95]
	v_cndmask_b32_e64 v237, v107, v119, s[94:95]
	v_mov_b32_dpp v238, v234 row_ror:8 row_mask:0xf bank_mask:0xf bound_ctrl:1
	v_mov_b32_dpp v239, v235 row_ror:8 row_mask:0xf bank_mask:0xf bound_ctrl:1
	v_mov_b32_dpp v240, v236 row_ror:8 row_mask:0xf bank_mask:0xf bound_ctrl:1
	v_mov_b32_dpp v241, v237 row_ror:8 row_mask:0xf bank_mask:0xf bound_ctrl:1
	v_cndmask_b32_e64 v116, v116, v238, s[94:95]
	v_cndmask_b32_e64 v117, v117, v239, s[94:95]
	v_cndmask_b32_e64 v118, v118, v240, s[94:95]
	v_cndmask_b32_e64 v119, v119, v241, s[94:95]
	v_cndmask_b32_e64 v104, v238, v104, s[94:95]
	v_cndmask_b32_e64 v105, v239, v105, s[94:95]
	v_cndmask_b32_e64 v106, v240, v106, s[94:95]
	v_cndmask_b32_e64 v107, v241, v107, s[94:95]
	s_waitcnt vmcnt(17)
	v_pk_add_f32 v[116:117], v[116:117], v[156:157]
	v_pk_add_f32 v[118:119], v[118:119], v[158:159]
	global_store_dwordx4 v218, v[116:119], s[50:51] offset:512
	global_load_dwordx4 v[156:159], v222, s[36:37] offset:512
	s_waitcnt vmcnt(18)
	v_pk_add_f32 v[104:105], v[104:105], v[160:161]
	v_pk_add_f32 v[106:107], v[106:107], v[162:163]
	global_store_dwordx4 v226, v[104:107], s[50:51] offset:512
	global_load_dwordx4 v[160:163], v230, s[36:37] offset:512
	v_cndmask_b32_e64 v234, v108, v112, s[94:95]
	v_cndmask_b32_e64 v235, v109, v113, s[94:95]
	v_cndmask_b32_e64 v236, v110, v114, s[94:95]
	v_cndmask_b32_e64 v237, v111, v115, s[94:95]
	v_mov_b32_dpp v238, v234 row_ror:8 row_mask:0xf bank_mask:0xf bound_ctrl:1
	v_mov_b32_dpp v239, v235 row_ror:8 row_mask:0xf bank_mask:0xf bound_ctrl:1
	v_mov_b32_dpp v240, v236 row_ror:8 row_mask:0xf bank_mask:0xf bound_ctrl:1
	v_mov_b32_dpp v241, v237 row_ror:8 row_mask:0xf bank_mask:0xf bound_ctrl:1
	v_cndmask_b32_e64 v112, v112, v238, s[94:95]
	v_cndmask_b32_e64 v113, v113, v239, s[94:95]
	v_cndmask_b32_e64 v114, v114, v240, s[94:95]
	v_cndmask_b32_e64 v115, v115, v241, s[94:95]
	v_cndmask_b32_e64 v108, v238, v108, s[94:95]
	v_cndmask_b32_e64 v109, v239, v109, s[94:95]
	v_cndmask_b32_e64 v110, v240, v110, s[94:95]
	v_cndmask_b32_e64 v111, v241, v111, s[94:95]
	s_waitcnt vmcnt(19)
	v_pk_add_f32 v[112:113], v[112:113], v[164:165]
	v_pk_add_f32 v[114:115], v[114:115], v[166:167]
	global_store_dwordx4 v219, v[112:115], s[50:51]
	global_load_dwordx4 v[164:167], v223, s[36:37]
	s_waitcnt vmcnt(20)
;     __device__ __forceinline__ void operator()(const pg8::f32x4 (&acc)[2][2][4][2], const pg8::Unit& u, int wr, int wc, int fr, int fq) const {
;     ...
;         for (int ai = 0; ai < 2; ++ai)
; #pragma unroll
;             for (int m = 0; m < 4; ++m) { const size_t off = (size_t)(row0 + ai * 128 + m * 16) * DM + col0;
; #pragma unroll
;                 for (int bj = 0; bj < 2; ++bj)
; #pragma unroll
;                     for (int n = 0; n < 2; ++n) { const size_t o2 = off + bj * 128 + n * 16; *(pg8::f32x4*)(out + o2) = *(const pg8::f32x4*)(x + o2) + acc[ai][bj][m][n]; }
;                 if (m & 1) asm volatile("" ::: "memory"); }
	v_pk_add_f32 v[108:109], v[108:109], v[168:169]
	v_pk_add_f32 v[110:111], v[110:111], v[170:171]
	global_store_dwordx4 v227, v[108:111], s[50:51]
	global_load_dwordx4 v[168:171], v231, s[36:37]
	v_cndmask_b32_e64 v234, v88, v100, s[94:95]
	v_cndmask_b32_e64 v235, v89, v101, s[94:95]
	v_cndmask_b32_e64 v236, v90, v102, s[94:95]
	v_cndmask_b32_e64 v237, v91, v103, s[94:95]
	v_mov_b32_dpp v238, v234 row_ror:8 row_mask:0xf bank_mask:0xf bound_ctrl:1
	v_mov_b32_dpp v239, v235 row_ror:8 row_mask:0xf bank_mask:0xf bound_ctrl:1
	v_mov_b32_dpp v240, v236 row_ror:8 row_mask:0xf bank_mask:0xf bound_ctrl:1
	v_mov_b32_dpp v241, v237 row_ror:8 row_mask:0xf bank_mask:0xf bound_ctrl:1
	v_cndmask_b32_e64 v100, v100, v238, s[94:95]
	v_cndmask_b32_e64 v101, v101, v239, s[94:95]
	v_cndmask_b32_e64 v102, v102, v240, s[94:95]
	v_cndmask_b32_e64 v103, v103, v241, s[94:95]
	v_cndmask_b32_e64 v88, v238, v88, s[94:95]
	v_cndmask_b32_e64 v89, v239, v89, s[94:95]
	v_cndmask_b32_e64 v90, v240, v90, s[94:95]
	v_cndmask_b32_e64 v91, v241, v91, s[94:95]
	s_waitcnt vmcnt(21)
	v_pk_add_f32 v[100:101], v[100:101], v[172:173]
	v_pk_add_f32 v[102:103], v[102:103], v[174:175]
	global_store_dwordx4 v219, v[100:103], s[50:51] offset:512
	global_load_dwordx4 v[172:175], v223, s[36:37] offset:512
	s_waitcnt vmcnt(22)
	v_pk_add_f32 v[88:89], v[88:89], v[176:177]
	v_pk_add_f32 v[90:91], v[90:91], v[178:179]
	global_store_dwordx4 v227, v[88:91], s[50:51] offset:512
	global_load_dwordx4 v[176:179], v231, s[36:37] offset:512
	v_cndmask_b32_e64 v234, v92, v96, s[94:95]
	v_cndmask_b32_e64 v235, v93, v97, s[94:95]
	v_cndmask_b32_e64 v236, v94, v98, s[94:95]
	v_cndmask_b32_e64 v237, v95, v99, s[94:95]
	v_mov_b32_dpp v238, v234 row_ror:8 row_mask:0xf bank_mask:0xf bound_ctrl:1
	v_mov_b32_dpp v239, v235 row_ror:8 row_mask:0xf bank_mask:0xf bound_ctrl:1
	v_mov_b32_dpp v240, v236 row_ror:8 row_mask:0xf bank_mask:0xf bound_ctrl:1
	v_mov_b32_dpp v241, v237 row_ror:8 row_mask:0xf bank_mask:0xf bound_ctrl:1
	v_cndmask_b32_e64 v96, v96, v238, s[94:95]
	v_cndmask_b32_e64 v97, v97, v239, s[94:95]
	v_cndmask_b32_e64 v98, v98, v240, s[94:95]
	v_cndmask_b32_e64 v99, v99, v241, s[94:95]
	v_cndmask_b32_e64 v92, v238, v92, s[94:95]
	v_cndmask_b32_e64 v93, v239, v93, s[94:95]
	v_cndmask_b32_e64 v94, v240, v94, s[94:95]
	v_cndmask_b32_e64 v95, v241, v95, s[94:95]
	s_waitcnt vmcnt(23)
	v_pk_add_f32 v[96:97], v[96:97], v[180:181]
	v_pk_add_f32 v[98:99], v[98:99], v[182:183]
	global_store_dwordx4 v220, v[96:99], s[50:51]
	global_load_dwordx4 v[180:183], v224, s[36:37]
	s_waitcnt vmcnt(24)
	v_pk_add_f32 v[92:93], v[92:93], v[184:185]
	v_pk_add_f32 v[94:95], v[94:95], v[186:187]
	global_store_dwordx4 v228, v[92:95], s[50:51]
	global_load_dwordx4 v[184:187], v232, s[36:37]
	v_cndmask_b32_e64 v234, v72, v84, s[94:95]
	v_cndmask_b32_e64 v235, v73, v85, s[94:95]
	v_cndmask_b32_e64 v236, v74, v86, s[94:95]
	v_cndmask_b32_e64 v237, v75, v87, s[94:95]
	v_mov_b32_dpp v238, v234 row_ror:8 row_mask:0xf bank_mask:0xf bound_ctrl:1
	v_mov_b32_dpp v239, v235 row_ror:8 row_mask:0xf bank_mask:0xf bound_ctrl:1
	v_mov_b32_dpp v240, v236 row_ror:8 row_mask:0xf bank_mask:0xf bound_ctrl:1
	v_mov_b32_dpp v241, v237 row_ror:8 row_mask:0xf bank_mask:0xf bound_ctrl:1
	v_cndmask_b32_e64 v84, v84, v238, s[94:95]
	v_cndmask_b32_e64 v85, v85, v239, s[94:95]
	v_cndmask_b32_e64 v86, v86, v240, s[94:95]
	v_cndmask_b32_e64 v87, v87, v241, s[94:95]
	v_cndmask_b32_e64 v72, v238, v72, s[94:95]
	v_cndmask_b32_e64 v73, v239, v73, s[94:95]
	v_cndmask_b32_e64 v74, v240, v74, s[94:95]
	v_cndmask_b32_e64 v75, v241, v75, s[94:95]
	s_waitcnt vmcnt(25)
	v_pk_add_f32 v[84:85], v[84:85], v[188:189]
	v_pk_add_f32 v[86:87], v[86:87], v[190:191]
	global_store_dwordx4 v220, v[84:87], s[50:51] offset:512
	global_load_dwordx4 v[188:191], v224, s[36:37] offset:512
	s_waitcnt vmcnt(26)
	v_pk_add_f32 v[72:73], v[72:73], v[192:193]
	v_pk_add_f32 v[74:75], v[74:75], v[194:195]
	global_store_dwordx4 v228, v[72:75], s[50:51] offset:512
	global_load_dwordx4 v[192:195], v232, s[36:37] offset:512
	v_cndmask_b32_e64 v234, v76, v80, s[94:95]
	v_cndmask_b32_e64 v235, v77, v81, s[94:95]
	v_cndmask_b32_e64 v236, v78, v82, s[94:95]
	v_cndmask_b32_e64 v237, v79, v83, s[94:95]
	v_mov_b32_dpp v238, v234 row_ror:8 row_mask:0xf bank_mask:0xf bound_ctrl:1
	v_mov_b32_dpp v239, v235 row_ror:8 row_mask:0xf bank_mask:0xf bound_ctrl:1
	v_mov_b32_dpp v240, v236 row_ror:8 row_mask:0xf bank_mask:0xf bound_ctrl:1
	v_mov_b32_dpp v241, v237 row_ror:8 row_mask:0xf bank_mask:0xf bound_ctrl:1
	v_cndmask_b32_e64 v80, v80, v238, s[94:95]
	v_cndmask_b32_e64 v81, v81, v239, s[94:95]
	v_cndmask_b32_e64 v82, v82, v240, s[94:95]
	v_cndmask_b32_e64 v83, v83, v241, s[94:95]
	v_cndmask_b32_e64 v76, v238, v76, s[94:95]
	v_cndmask_b32_e64 v77, v239, v77, s[94:95]
	v_cndmask_b32_e64 v78, v240, v78, s[94:95]
	v_cndmask_b32_e64 v79, v241, v79, s[94:95]
	s_waitcnt vmcnt(27)
	v_pk_add_f32 v[80:81], v[80:81], v[196:197]
	v_pk_add_f32 v[82:83], v[82:83], v[198:199]
	global_store_dwordx4 v221, v[80:83], s[50:51]
	global_load_dwordx4 v[196:199], v225, s[36:37]
	s_waitcnt vmcnt(28)
	v_pk_add_f32 v[76:77], v[76:77], v[200:201]
	v_pk_add_f32 v[78:79], v[78:79], v[202:203]
	global_store_dwordx4 v229, v[76:79], s[50:51]
	global_load_dwordx4 v[200:203], v233, s[36:37]
	v_cndmask_b32_e64 v234, v64, v68, s[94:95]
	v_cndmask_b32_e64 v235, v65, v69, s[94:95]
	v_cndmask_b32_e64 v236, v66, v70, s[94:95]
	v_cndmask_b32_e64 v237, v67, v71, s[94:95]
	v_mov_b32_dpp v238, v234 row_ror:8 row_mask:0xf bank_mask:0xf bound_ctrl:1
	v_mov_b32_dpp v239, v235 row_ror:8 row_mask:0xf bank_mask:0xf bound_ctrl:1
	v_mov_b32_dpp v240, v236 row_ror:8 row_mask:0xf bank_mask:0xf bound_ctrl:1
	v_mov_b32_dpp v241, v237 row_ror:8 row_mask:0xf bank_mask:0xf bound_ctrl:1
	v_cndmask_b32_e64 v68, v68, v238, s[94:95]
	v_cndmask_b32_e64 v69, v69, v239, s[94:95]
	v_cndmask_b32_e64 v70, v70, v240, s[94:95]
	v_cndmask_b32_e64 v71, v71, v241, s[94:95]
	v_cndmask_b32_e64 v64, v238, v64, s[94:95]
	v_cndmask_b32_e64 v65, v239, v65, s[94:95]
	v_cndmask_b32_e64 v66, v240, v66, s[94:95]
	v_cndmask_b32_e64 v67, v241, v67, s[94:95]
	s_waitcnt vmcnt(29)
;     __device__ __forceinline__ void operator()(const pg8::f32x4 (&acc)[2][2][4][2], const pg8::Unit& u, int wr, int wc, int fr, int fq) const {
;     ...
;         for (int ai = 0; ai < 2; ++ai)
; #pragma unroll
;             for (int m = 0; m < 4; ++m) { const size_t off = (size_t)(row0 + ai * 128 + m * 16) * DM + col0;
; #pragma unroll
;                 for (int bj = 0; bj < 2; ++bj)
; #pragma unroll
;                     for (int n = 0; n < 2; ++n) { const size_t o2 = off + bj * 128 + n * 16; *(pg8::f32x4*)(out + o2) = *(const pg8::f32x4*)(x + o2) + acc[ai][bj][m][n]; }
;                 if (m & 1) asm volatile("" ::: "memory"); }
	v_pk_add_f32 v[68:69], v[68:69], v[204:205]
	v_pk_add_f32 v[70:71], v[70:71], v[206:207]
	global_store_dwordx4 v221, v[68:71], s[50:51] offset:512
	global_load_dwordx4 v[204:207], v225, s[36:37] offset:512
	s_waitcnt vmcnt(30)
	v_pk_add_f32 v[64:65], v[64:65], v[208:209]
	v_pk_add_f32 v[66:67], v[66:67], v[210:211]
	global_store_dwordx4 v229, v[64:67], s[50:51] offset:512
	global_load_dwordx4 v[208:211], v233, s[36:37] offset:512
	v_cndmask_b32_e64 v234, v56, v60, s[94:95]
	v_cndmask_b32_e64 v235, v57, v61, s[94:95]
	v_cndmask_b32_e64 v236, v58, v62, s[94:95]
	v_cndmask_b32_e64 v237, v59, v63, s[94:95]
	v_mov_b32_dpp v238, v234 row_ror:8 row_mask:0xf bank_mask:0xf bound_ctrl:1
	v_mov_b32_dpp v239, v235 row_ror:8 row_mask:0xf bank_mask:0xf bound_ctrl:1
	v_mov_b32_dpp v240, v236 row_ror:8 row_mask:0xf bank_mask:0xf bound_ctrl:1
	v_mov_b32_dpp v241, v237 row_ror:8 row_mask:0xf bank_mask:0xf bound_ctrl:1
	v_cndmask_b32_e64 v60, v60, v238, s[94:95]
	v_cndmask_b32_e64 v61, v61, v239, s[94:95]
	v_cndmask_b32_e64 v62, v62, v240, s[94:95]
	v_cndmask_b32_e64 v63, v63, v241, s[94:95]
	v_cndmask_b32_e64 v56, v238, v56, s[94:95]
	v_cndmask_b32_e64 v57, v239, v57, s[94:95]
	v_cndmask_b32_e64 v58, v240, v58, s[94:95]
	v_cndmask_b32_e64 v59, v241, v59, s[94:95]
	s_waitcnt vmcnt(30)
	v_pk_add_f32 v[60:61], v[60:61], v[142:143]
	v_pk_add_f32 v[62:63], v[62:63], v[144:145]
	global_store_dwordx4 v222, v[60:63], s[50:51]
	s_waitcnt vmcnt(29)
	v_pk_add_f32 v[56:57], v[56:57], v[146:147]
	v_pk_add_f32 v[58:59], v[58:59], v[148:149]
	global_store_dwordx4 v230, v[56:59], s[50:51]
	v_cndmask_b32_e64 v234, v40, v52, s[94:95]
	v_cndmask_b32_e64 v235, v41, v53, s[94:95]
	v_cndmask_b32_e64 v236, v42, v54, s[94:95]
	v_cndmask_b32_e64 v237, v43, v55, s[94:95]
	v_mov_b32_dpp v238, v234 row_ror:8 row_mask:0xf bank_mask:0xf bound_ctrl:1
	v_mov_b32_dpp v239, v235 row_ror:8 row_mask:0xf bank_mask:0xf bound_ctrl:1
	v_mov_b32_dpp v240, v236 row_ror:8 row_mask:0xf bank_mask:0xf bound_ctrl:1
	v_mov_b32_dpp v241, v237 row_ror:8 row_mask:0xf bank_mask:0xf bound_ctrl:1
	v_cndmask_b32_e64 v52, v52, v238, s[94:95]
	v_cndmask_b32_e64 v53, v53, v239, s[94:95]
	v_cndmask_b32_e64 v54, v54, v240, s[94:95]
	v_cndmask_b32_e64 v55, v55, v241, s[94:95]
	v_cndmask_b32_e64 v40, v238, v40, s[94:95]
	v_cndmask_b32_e64 v41, v239, v41, s[94:95]
	v_cndmask_b32_e64 v42, v240, v42, s[94:95]
	v_cndmask_b32_e64 v43, v241, v43, s[94:95]
	s_waitcnt vmcnt(28)
	v_pk_add_f32 v[52:53], v[52:53], v[156:157]
	v_pk_add_f32 v[54:55], v[54:55], v[158:159]
	global_store_dwordx4 v222, v[52:55], s[50:51] offset:512
	s_waitcnt vmcnt(27)
	v_pk_add_f32 v[40:41], v[40:41], v[160:161]
	v_pk_add_f32 v[42:43], v[42:43], v[162:163]
	global_store_dwordx4 v230, v[40:43], s[50:51] offset:512
	v_cndmask_b32_e64 v234, v44, v48, s[94:95]
	v_cndmask_b32_e64 v235, v45, v49, s[94:95]
	v_cndmask_b32_e64 v236, v46, v50, s[94:95]
	v_cndmask_b32_e64 v237, v47, v51, s[94:95]
	v_mov_b32_dpp v238, v234 row_ror:8 row_mask:0xf bank_mask:0xf bound_ctrl:1
	v_mov_b32_dpp v239, v235 row_ror:8 row_mask:0xf bank_mask:0xf bound_ctrl:1
	v_mov_b32_dpp v240, v236 row_ror:8 row_mask:0xf bank_mask:0xf bound_ctrl:1
	v_mov_b32_dpp v241, v237 row_ror:8 row_mask:0xf bank_mask:0xf bound_ctrl:1
	v_cndmask_b32_e64 v48, v48, v238, s[94:95]
	v_cndmask_b32_e64 v49, v49, v239, s[94:95]
	v_cndmask_b32_e64 v50, v50, v240, s[94:95]
	v_cndmask_b32_e64 v51, v51, v241, s[94:95]
	v_cndmask_b32_e64 v44, v238, v44, s[94:95]
	v_cndmask_b32_e64 v45, v239, v45, s[94:95]
	v_cndmask_b32_e64 v46, v240, v46, s[94:95]
	v_cndmask_b32_e64 v47, v241, v47, s[94:95]
	s_waitcnt vmcnt(26)
	v_pk_add_f32 v[48:49], v[48:49], v[164:165]
	v_pk_add_f32 v[50:51], v[50:51], v[166:167]
	global_store_dwordx4 v223, v[48:51], s[50:51]
	s_waitcnt vmcnt(25)
	v_pk_add_f32 v[44:45], v[44:45], v[168:169]
	v_pk_add_f32 v[46:47], v[46:47], v[170:171]
	global_store_dwordx4 v231, v[44:47], s[50:51]
	v_cndmask_b32_e64 v234, v24, v36, s[94:95]
	v_cndmask_b32_e64 v235, v25, v37, s[94:95]
	v_cndmask_b32_e64 v236, v26, v38, s[94:95]
	v_cndmask_b32_e64 v237, v27, v39, s[94:95]
	v_mov_b32_dpp v238, v234 row_ror:8 row_mask:0xf bank_mask:0xf bound_ctrl:1
	v_mov_b32_dpp v239, v235 row_ror:8 row_mask:0xf bank_mask:0xf bound_ctrl:1
	v_mov_b32_dpp v240, v236 row_ror:8 row_mask:0xf bank_mask:0xf bound_ctrl:1
	v_mov_b32_dpp v241, v237 row_ror:8 row_mask:0xf bank_mask:0xf bound_ctrl:1
	v_cndmask_b32_e64 v36, v36, v238, s[94:95]
	v_cndmask_b32_e64 v37, v37, v239, s[94:95]
	v_cndmask_b32_e64 v38, v38, v240, s[94:95]
	v_cndmask_b32_e64 v39, v39, v241, s[94:95]
	v_cndmask_b32_e64 v24, v238, v24, s[94:95]
	v_cndmask_b32_e64 v25, v239, v25, s[94:95]
	v_cndmask_b32_e64 v26, v240, v26, s[94:95]
	v_cndmask_b32_e64 v27, v241, v27, s[94:95]
	s_waitcnt vmcnt(24)
	v_pk_add_f32 v[36:37], v[36:37], v[172:173]
	v_pk_add_f32 v[38:39], v[38:39], v[174:175]
	global_store_dwordx4 v223, v[36:39], s[50:51] offset:512
	s_waitcnt vmcnt(23)
; #define PG8_BAR __builtin_amdgcn_s_barrier()
; template <class Epi, class Sched, bool ALIGN_EPI = false, bool SP2 = false>
; __device__ __forceinline__ void gemm_phase(PG8_LAS unsigned char* lds, const Gemm g, const Sched& S, const Epi& E) {
;     ...
;         if constexpr (ALIGN_EPI) { if (wr == 0) PG8_BAR; }
;         if constexpr (!Epi::AFTER_DRAIN) { E(acc, cur, wr, wc, fr, fq); S.done(cur); }
;         if (!has_next) break;
; #pragma unroll
;         for (int a = 0; a < 2; ++a)
; #pragma unroll
;             for (int b = 0; b < 2; ++b)
; #pragma unroll
;                 for (int m = 0; m < 4; ++m)
; #pragma unroll
;                     for (int n = 0; n < 2; ++n) acc[a][b][m][n] = (f32x4){0.f, 0.f, 0.f, 0.f};
;         cur = nxt; cA = nA; cB = nB; ++ui;
;         if constexpr (ALIGN_EPI) { if (wr == 1) PG8_BAR; }
;     __device__ __forceinline__ void operator()(const pg8::f32x4 (&acc)[2][2][4][2], const pg8::Unit& u, int wr, int wc, int fr, int fq) const {
;     ...
;         for (int ai = 0; ai < 2; ++ai)
; #pragma unroll
;             for (int m = 0; m < 4; ++m) { const size_t off = (size_t)(row0 + ai * 128 + m * 16) * DM + col0;
; #pragma unroll
;                 for (int bj = 0; bj < 2; ++bj)
; #pragma unroll
;                     for (int n = 0; n < 2; ++n) { const size_t o2 = off + bj * 128 + n * 16; *(pg8::f32x4*)(out + o2) = *(const pg8::f32x4*)(x + o2) + acc[ai][bj][m][n]; }
;                 if (m & 1) asm volatile("" ::: "memory"); }
	v_pk_add_f32 v[24:25], v[24:25], v[176:177]
	v_pk_add_f32 v[26:27], v[26:27], v[178:179]
	global_store_dwordx4 v231, v[24:27], s[50:51] offset:512
	v_cndmask_b32_e64 v234, v28, v32, s[94:95]
	v_cndmask_b32_e64 v235, v29, v33, s[94:95]
	v_cndmask_b32_e64 v236, v30, v34, s[94:95]
	v_cndmask_b32_e64 v237, v31, v35, s[94:95]
	v_mov_b32_dpp v238, v234 row_ror:8 row_mask:0xf bank_mask:0xf bound_ctrl:1
	v_mov_b32_dpp v239, v235 row_ror:8 row_mask:0xf bank_mask:0xf bound_ctrl:1
	v_mov_b32_dpp v240, v236 row_ror:8 row_mask:0xf bank_mask:0xf bound_ctrl:1
	v_mov_b32_dpp v241, v237 row_ror:8 row_mask:0xf bank_mask:0xf bound_ctrl:1
	v_cndmask_b32_e64 v32, v32, v238, s[94:95]
	v_cndmask_b32_e64 v33, v33, v239, s[94:95]
	v_cndmask_b32_e64 v34, v34, v240, s[94:95]
	v_cndmask_b32_e64 v35, v35, v241, s[94:95]
	v_cndmask_b32_e64 v28, v238, v28, s[94:95]
	v_cndmask_b32_e64 v29, v239, v29, s[94:95]
	v_cndmask_b32_e64 v30, v240, v30, s[94:95]
	v_cndmask_b32_e64 v31, v241, v31, s[94:95]
	s_waitcnt vmcnt(22)
	v_pk_add_f32 v[32:33], v[32:33], v[180:181]
	v_pk_add_f32 v[34:35], v[34:35], v[182:183]
	global_store_dwordx4 v224, v[32:35], s[50:51]
	s_waitcnt vmcnt(21)
	v_pk_add_f32 v[28:29], v[28:29], v[184:185]
	v_pk_add_f32 v[30:31], v[30:31], v[186:187]
	global_store_dwordx4 v232, v[28:31], s[50:51]
	v_cndmask_b32_e64 v234, v8, v20, s[94:95]
	v_cndmask_b32_e64 v235, v9, v21, s[94:95]
	v_cndmask_b32_e64 v236, v10, v22, s[94:95]
	v_cndmask_b32_e64 v237, v11, v23, s[94:95]
	v_mov_b32_dpp v238, v234 row_ror:8 row_mask:0xf bank_mask:0xf bound_ctrl:1
	v_mov_b32_dpp v239, v235 row_ror:8 row_mask:0xf bank_mask:0xf bound_ctrl:1
	v_mov_b32_dpp v240, v236 row_ror:8 row_mask:0xf bank_mask:0xf bound_ctrl:1
	v_mov_b32_dpp v241, v237 row_ror:8 row_mask:0xf bank_mask:0xf bound_ctrl:1
	v_cndmask_b32_e64 v20, v20, v238, s[94:95]
	v_cndmask_b32_e64 v21, v21, v239, s[94:95]
	v_cndmask_b32_e64 v22, v22, v240, s[94:95]
	v_cndmask_b32_e64 v23, v23, v241, s[94:95]
	v_cndmask_b32_e64 v8, v238, v8, s[94:95]
	v_cndmask_b32_e64 v9, v239, v9, s[94:95]
	v_cndmask_b32_e64 v10, v240, v10, s[94:95]
	v_cndmask_b32_e64 v11, v241, v11, s[94:95]
	s_waitcnt vmcnt(20)
	v_pk_add_f32 v[20:21], v[20:21], v[188:189]
	v_pk_add_f32 v[22:23], v[22:23], v[190:191]
	global_store_dwordx4 v224, v[20:23], s[50:51] offset:512
	s_waitcnt vmcnt(19)
	v_pk_add_f32 v[8:9], v[8:9], v[192:193]
	v_pk_add_f32 v[10:11], v[10:11], v[194:195]
	global_store_dwordx4 v232, v[8:11], s[50:51] offset:512
	v_cndmask_b32_e64 v234, v12, v16, s[94:95]
	v_cndmask_b32_e64 v235, v13, v17, s[94:95]
	v_cndmask_b32_e64 v236, v14, v18, s[94:95]
	v_cndmask_b32_e64 v237, v15, v19, s[94:95]
	v_mov_b32_dpp v238, v234 row_ror:8 row_mask:0xf bank_mask:0xf bound_ctrl:1
	v_mov_b32_dpp v239, v235 row_ror:8 row_mask:0xf bank_mask:0xf bound_ctrl:1
	v_mov_b32_dpp v240, v236 row_ror:8 row_mask:0xf bank_mask:0xf bound_ctrl:1
	v_mov_b32_dpp v241, v237 row_ror:8 row_mask:0xf bank_mask:0xf bound_ctrl:1
	v_cndmask_b32_e64 v16, v16, v238, s[94:95]
	v_cndmask_b32_e64 v17, v17, v239, s[94:95]
	v_cndmask_b32_e64 v18, v18, v240, s[94:95]
	v_cndmask_b32_e64 v19, v19, v241, s[94:95]
	v_cndmask_b32_e64 v12, v238, v12, s[94:95]
	v_cndmask_b32_e64 v13, v239, v13, s[94:95]
	v_cndmask_b32_e64 v14, v240, v14, s[94:95]
	v_cndmask_b32_e64 v15, v241, v15, s[94:95]
	s_waitcnt vmcnt(18)
	v_pk_add_f32 v[16:17], v[16:17], v[196:197]
	v_pk_add_f32 v[18:19], v[18:19], v[198:199]
	global_store_dwordx4 v225, v[16:19], s[50:51]
	s_waitcnt vmcnt(17)
	v_pk_add_f32 v[12:13], v[12:13], v[200:201]
	v_pk_add_f32 v[14:15], v[14:15], v[202:203]
	global_store_dwordx4 v233, v[12:15], s[50:51]
	v_cndmask_b32_e64 v234, v0, v4, s[94:95]
	v_cndmask_b32_e64 v235, v1, v5, s[94:95]
	v_cndmask_b32_e64 v236, v2, v6, s[94:95]
	v_cndmask_b32_e64 v237, v3, v7, s[94:95]
	v_mov_b32_dpp v238, v234 row_ror:8 row_mask:0xf bank_mask:0xf bound_ctrl:1
	v_mov_b32_dpp v239, v235 row_ror:8 row_mask:0xf bank_mask:0xf bound_ctrl:1
	v_mov_b32_dpp v240, v236 row_ror:8 row_mask:0xf bank_mask:0xf bound_ctrl:1
	v_mov_b32_dpp v241, v237 row_ror:8 row_mask:0xf bank_mask:0xf bound_ctrl:1
	v_cndmask_b32_e64 v4, v4, v238, s[94:95]
	v_cndmask_b32_e64 v5, v5, v239, s[94:95]
	v_cndmask_b32_e64 v6, v6, v240, s[94:95]
	v_cndmask_b32_e64 v7, v7, v241, s[94:95]
	v_cndmask_b32_e64 v0, v238, v0, s[94:95]
	v_cndmask_b32_e64 v1, v239, v1, s[94:95]
	v_cndmask_b32_e64 v2, v240, v2, s[94:95]
	v_cndmask_b32_e64 v3, v241, v3, s[94:95]
	s_waitcnt vmcnt(16)
	v_pk_add_f32 v[4:5], v[4:5], v[204:205]
	v_pk_add_f32 v[6:7], v[6:7], v[206:207]
	global_store_dwordx4 v225, v[4:7], s[50:51] offset:512
	s_waitcnt vmcnt(15)
	v_pk_add_f32 v[0:1], v[0:1], v[208:209]
	v_pk_add_f32 v[2:3], v[2:3], v[210:211]
	global_store_dwordx4 v233, v[0:3], s[50:51] offset:512
	s_cbranch_vccnz .LBB0_469
	s_andn2_b64 vcc, exec, s[0:1]
	s_cbranch_vccnz .LBB0_468
	s_barrier
	s_branch .LBB0_468

; #define LAS __attribute__((address_space(3)))
; __global__ void __launch_bounds__(512, 2) mega_fwd(Args a) {
;     extern __shared__ __attribute__((aligned(16))) unsigned char lds_raw[];
;     LAS unsigned char* lds = (LAS unsigned char*)lds_raw;
;     cg::grid_group grid = cg::this_grid();
;     const int tid = threadIdx.x, lane = tid & 63, wave = __builtin_amdgcn_readfirstlane(tid >> 6);
	.amdhsa_kernel _Z8mega_fwd4Args
		.amdhsa_group_segment_fixed_size 0
		.amdhsa_private_segment_fixed_size 0
		.amdhsa_kernarg_size 328
		.amdhsa_user_sgpr_count 2
		.amdhsa_user_sgpr_dispatch_ptr 0
		.amdhsa_user_sgpr_queue_ptr 0
		.amdhsa_user_sgpr_kernarg_segment_ptr 1
		.amdhsa_user_sgpr_dispatch_id 0
		.amdhsa_user_sgpr_kernarg_preload_length 0
		.amdhsa_user_sgpr_kernarg_preload_offset 0
		.amdhsa_user_sgpr_private_segment_size 0
		.amdhsa_uses_dynamic_stack 0
		.amdhsa_enable_private_segment 0
		.amdhsa_system_sgpr_workgroup_id_x 1
		.amdhsa_system_sgpr_workgroup_id_y 0
		.amdhsa_system_sgpr_workgroup_id_z 0
		.amdhsa_system_sgpr_workgroup_info 0
		.amdhsa_system_vgpr_workitem_id 2
		.amdhsa_next_free_vgpr 248
		.amdhsa_next_free_sgpr 102
		.amdhsa_accum_offset 248
		.amdhsa_reserve_vcc 1
		.amdhsa_float_round_mode_32 0
		.amdhsa_float_round_mode_16_64 0
		.amdhsa_float_denorm_mode_32 3
		.amdhsa_float_denorm_mode_16_64 3
		.amdhsa_dx10_clamp 1
		.amdhsa_ieee_mode 1
		.amdhsa_fp16_overflow 0
		.amdhsa_tg_split 0
		.amdhsa_exception_fp_ieee_invalid_op 0
		.amdhsa_exception_fp_denorm_src 0
		.amdhsa_exception_fp_ieee_div_zero 0
		.amdhsa_exception_fp_ieee_overflow 0
		.amdhsa_exception_fp_ieee_underflow 0
		.amdhsa_exception_fp_ieee_inexact 0
		.amdhsa_exception_int_div_zero 0
	.end_amdhsa_kernel

; #define LAS __attribute__((address_space(3)))
; __global__ void __launch_bounds__(512, 2) mega_fwd(Args a) {
;     extern __shared__ __attribute__((aligned(16))) unsigned char lds_raw[];
;     LAS unsigned char* lds = (LAS unsigned char*)lds_raw;
;     cg::grid_group grid = cg::this_grid();
;     const int tid = threadIdx.x, lane = tid & 63, wave = __builtin_amdgcn_readfirstlane(tid >> 6);
amdhsa.kernels:
  - .agpr_count:     0
    .args:
      - .offset:         0
        .size:           72
        .value_kind:     by_value
      - .offset:         72
        .size:           4
        .value_kind:     hidden_block_count_x
      - .offset:         76
        .size:           4
        .value_kind:     hidden_block_count_y
      - .offset:         80
        .size:           4
        .value_kind:     hidden_block_count_z
      - .offset:         84
        .size:           2
        .value_kind:     hidden_group_size_x
      - .offset:         86
        .size:           2
        .value_kind:     hidden_group_size_y
      - .offset:         88
        .size:           2
        .value_kind:     hidden_group_size_z
      - .offset:         90
        .size:           2
        .value_kind:     hidden_remainder_x
      - .offset:         92
        .size:           2
        .value_kind:     hidden_remainder_y
      - .offset:         94
        .size:           2
        .value_kind:     hidden_remainder_z
      - .offset:         112
        .size:           8
        .value_kind:     hidden_global_offset_x
      - .offset:         120
        .size:           8
        .value_kind:     hidden_global_offset_y
      - .offset:         128
        .size:           8
        .value_kind:     hidden_global_offset_z
      - .offset:         136
        .size:           2
        .value_kind:     hidden_grid_dims
      - .offset:         160
        .size:           8
        .value_kind:     hidden_multigrid_sync_arg
      - .offset:         192
        .size:           4
        .value_kind:     hidden_dynamic_lds_size
    .group_segment_fixed_size: 0
    .kernarg_segment_align: 8
    .kernarg_segment_size: 328
    .language:       OpenCL C
    .language_version:
      - 2
      - 0
    .max_flat_workgroup_size: 512
    .name:           _Z8mega_fwd4Args
    .private_segment_fixed_size: 0
    .sgpr_count:     108
    .sgpr_spill_count: 0
    .symbol:         _Z8mega_fwd4Args.kd
    .uniform_work_group_size: 1
    .uses_dynamic_stack: false
    .vgpr_count:     248
    .vgpr_spill_count: 0
    .wavefront_size: 64
